# nt residual epilogue + P0a silu staging loads batched + cooperative-groups sync after P0a replaced by the kernel's own XCD grid barrier
# speedup vs baseline: 1.0068x; 1.0068x over previous
; __device__ __forceinline__ void phase_p0a(const Args& a, LAS unsigned char* lds, int bid, int G, int wave) {
;     ...
;     if (bid < 288) {
;         for (int i = tid; i < NBATCH * D; i += NTHREADS) { const int b = i >> 10, k = i & 1023; const float c = b < 8 ? a.cp[b * D + k] : a.cs[(b - 8) * D + k]; sc[i] = c / (1.0f + __expf(-c)); }
;         __syncthreads();
.LBB0_8:
	v_writelane_b32 v251, s40, 19
	s_lshr_b32 s14, s19, 6
	s_cmp_eq_u32 s86, 0
	v_writelane_b32 v251, s41, 20
	v_writelane_b32 v251, s42, 21
	v_writelane_b32 v251, s43, 22
	v_writelane_b32 v251, s44, 23
	v_writelane_b32 v251, s45, 24
	v_writelane_b32 v251, s46, 25
	v_writelane_b32 v251, s47, 26
	v_writelane_b32 v251, s48, 27
	v_writelane_b32 v251, s49, 28
	v_writelane_b32 v251, s50, 29
	v_writelane_b32 v251, s51, 30
	s_cselect_b64 s[0:1], -1, 0
	s_cmp_gt_i32 s87, 1
	v_writelane_b32 v251, s52, 31
	s_cselect_b64 s[4:5], -1, 0
	v_writelane_b32 v251, s53, 32
	s_and_b64 s[0:1], s[0:1], s[4:5]
	v_writelane_b32 v251, s54, 33
	s_andn2_b64 vcc, exec, s[0:1]
	v_writelane_b32 v251, s55, 34
	s_cbranch_vccnz .LBB0_81
	s_mul_i32 s1, s14, 0x2800
	s_and_b32 s0, s19, 0xffffffc0
	s_add_i32 s2, s1, 0
	v_readlane_b32 s1, v251, 0
	v_mbcnt_lo_u32_b32 v4, -1, 0
	v_mbcnt_hi_u32_b32 v4, -1, v4
	s_cmpk_gt_i32 s1, 0x11f
	v_add_u32_e32 v2, s0, v4
	s_cbranch_scc1 .LBB0_25
	s_movk_i32 s0, 0x27ff
	v_cmp_lt_i32_e32 vcc, s0, v2
	v_lshlrev_b32_e32 v5, 2, v4
	s_and_saveexec_b64 s[0:1], vcc
	s_xor_b64 s[0:1], exec, s[0:1]
	v_lshl_add_u32 v12, s14, 8, v5
	s_andn2_saveexec_b64 s[0:1], s[0:1]
	s_cbranch_execz .LBB0_18
	v_ashrrev_i32_e32 v3, 31, v2
	v_lshl_add_u32 v12, s14, 8, v5
	v_lshl_add_u64 v[6:7], v[2:3], 2, s[44:45]
	v_lshl_add_u64 v[10:11], v[2:3], 2, s[46:47]
	s_mov_b64 s[6:7], 0x1000
	global_load_dword v16, v[6:7], off
	global_load_dword v17, v[6:7], off offset:2048
	v_lshl_add_u64 v[6:7], v[6:7], 0, s[6:7]
	global_load_dword v18, v[6:7], off
	global_load_dword v19, v[6:7], off offset:2048
	v_lshl_add_u64 v[6:7], v[6:7], 0, s[6:7]
	global_load_dword v20, v[6:7], off
	global_load_dword v21, v[6:7], off offset:2048
	v_lshl_add_u64 v[6:7], v[6:7], 0, s[6:7]
	global_load_dword v22, v[6:7], off
	global_load_dword v23, v[6:7], off offset:2048
	v_lshl_add_u64 v[6:7], v[6:7], 0, s[6:7]
	global_load_dword v24, v[6:7], off
	global_load_dword v25, v[6:7], off offset:2048
	v_lshl_add_u64 v[6:7], v[6:7], 0, s[6:7]
	global_load_dword v26, v[6:7], off
	global_load_dword v27, v[6:7], off offset:2048
	v_lshl_add_u64 v[6:7], v[6:7], 0, s[6:7]
	global_load_dword v28, v[6:7], off
	global_load_dword v29, v[6:7], off offset:2048
	v_lshl_add_u64 v[6:7], v[6:7], 0, s[6:7]
	global_load_dword v30, v[6:7], off
	global_load_dword v31, v[6:7], off offset:2048
	global_load_dword v32, v[10:11], off
	global_load_dword v33, v[10:11], off offset:2048
	v_lshl_add_u64 v[10:11], v[10:11], 0, s[6:7]
	global_load_dword v34, v[10:11], off
	global_load_dword v35, v[10:11], off offset:2048
	v_add_u32_e32 v3, 0, v12
	s_waitcnt vmcnt(19)
	v_mul_f32_e32 v36, 0xbfb8aa3b, v16
	v_exp_f32_e32 v36, v36
	s_nop 0
	v_add_f32_e32 v41, 1.0, v36
	v_div_scale_f32 v36, s[8:9], v41, v41, v16
	v_rcp_f32_e32 v37, v36
	v_div_scale_f32 v38, vcc, v16, v41, v16
	v_fma_f32 v39, -v36, v37, 1.0
	v_fmac_f32_e32 v37, v39, v37
	v_mul_f32_e32 v39, v38, v37
	v_fma_f32 v40, -v36, v39, v38
	v_fmac_f32_e32 v39, v40, v37
	v_fma_f32 v36, -v36, v39, v38
	v_div_fmas_f32 v36, v36, v37, v39
	v_div_fixup_f32 v41, v36, v41, v16
	ds_write_b32 v3, v41
	s_waitcnt vmcnt(18)
	v_mul_f32_e32 v36, 0xbfb8aa3b, v17
	v_exp_f32_e32 v36, v36
	s_nop 0
	v_add_f32_e32 v41, 1.0, v36
	v_div_scale_f32 v36, s[8:9], v41, v41, v17
	v_rcp_f32_e32 v37, v36
	v_div_scale_f32 v38, vcc, v17, v41, v17
	v_fma_f32 v39, -v36, v37, 1.0
	v_fmac_f32_e32 v37, v39, v37
	v_mul_f32_e32 v39, v38, v37
	v_fma_f32 v40, -v36, v39, v38
	v_fmac_f32_e32 v39, v40, v37
	v_fma_f32 v36, -v36, v39, v38
	v_div_fmas_f32 v36, v36, v37, v39
	v_div_fixup_f32 v41, v36, v41, v17
	ds_write_b32 v3, v41 offset:2048
	s_waitcnt vmcnt(17)
	v_mul_f32_e32 v36, 0xbfb8aa3b, v18
	v_exp_f32_e32 v36, v36
	s_nop 0
	v_add_f32_e32 v41, 1.0, v36
	v_div_scale_f32 v36, s[8:9], v41, v41, v18
	v_rcp_f32_e32 v37, v36
	v_div_scale_f32 v38, vcc, v18, v41, v18
	v_fma_f32 v39, -v36, v37, 1.0
	v_fmac_f32_e32 v37, v39, v37
	v_mul_f32_e32 v39, v38, v37
	v_fma_f32 v40, -v36, v39, v38
	v_fmac_f32_e32 v39, v40, v37
	v_fma_f32 v36, -v36, v39, v38
	v_div_fmas_f32 v36, v36, v37, v39
	v_div_fixup_f32 v41, v36, v41, v18
	ds_write_b32 v3, v41 offset:4096
	s_waitcnt vmcnt(16)
	v_mul_f32_e32 v36, 0xbfb8aa3b, v19
	v_exp_f32_e32 v36, v36
	s_nop 0
	v_add_f32_e32 v41, 1.0, v36
	v_div_scale_f32 v36, s[8:9], v41, v41, v19
	v_rcp_f32_e32 v37, v36
	v_div_scale_f32 v38, vcc, v19, v41, v19
	v_fma_f32 v39, -v36, v37, 1.0
	v_fmac_f32_e32 v37, v39, v37
	v_mul_f32_e32 v39, v38, v37
	v_fma_f32 v40, -v36, v39, v38
	v_fmac_f32_e32 v39, v40, v37
	v_fma_f32 v36, -v36, v39, v38
	v_div_fmas_f32 v36, v36, v37, v39
	v_div_fixup_f32 v41, v36, v41, v19
	ds_write_b32 v3, v41 offset:6144
	s_waitcnt vmcnt(15)
	v_mul_f32_e32 v36, 0xbfb8aa3b, v20
	v_exp_f32_e32 v36, v36
	s_nop 0
	v_add_f32_e32 v41, 1.0, v36
	v_div_scale_f32 v36, s[8:9], v41, v41, v20
	v_rcp_f32_e32 v37, v36
	v_div_scale_f32 v38, vcc, v20, v41, v20
	v_fma_f32 v39, -v36, v37, 1.0
	v_fmac_f32_e32 v37, v39, v37
	v_mul_f32_e32 v39, v38, v37
	v_fma_f32 v40, -v36, v39, v38
	v_fmac_f32_e32 v39, v40, v37
	v_fma_f32 v36, -v36, v39, v38
	v_div_fmas_f32 v36, v36, v37, v39
	v_div_fixup_f32 v41, v36, v41, v20
	ds_write_b32 v3, v41 offset:8192
	s_waitcnt vmcnt(14)
	v_mul_f32_e32 v36, 0xbfb8aa3b, v21
	v_exp_f32_e32 v36, v36
	s_nop 0
	v_add_f32_e32 v41, 1.0, v36
	v_div_scale_f32 v36, s[8:9], v41, v41, v21
	v_rcp_f32_e32 v37, v36
	v_div_scale_f32 v38, vcc, v21, v41, v21
	v_fma_f32 v39, -v36, v37, 1.0
	v_fmac_f32_e32 v37, v39, v37
	v_mul_f32_e32 v39, v38, v37
	v_fma_f32 v40, -v36, v39, v38
	v_fmac_f32_e32 v39, v40, v37
	v_fma_f32 v36, -v36, v39, v38
	v_div_fmas_f32 v36, v36, v37, v39
	v_div_fixup_f32 v41, v36, v41, v21
	ds_write_b32 v3, v41 offset:10240
	s_waitcnt vmcnt(13)
; __device__ __forceinline__ void phase_p0a(const Args& a, LAS unsigned char* lds, int bid, int G, int wave) {
;     ...
;         for (int i = tid; i < NBATCH * D; i += NTHREADS) { const int b = i >> 10, k = i & 1023; const float c = b < 8 ? a.cp[b * D + k] : a.cs[(b - 8) * D + k]; sc[i] = c / (1.0f + __expf(-c)); }
	v_mul_f32_e32 v36, 0xbfb8aa3b, v22
	v_exp_f32_e32 v36, v36
	s_nop 0
	v_add_f32_e32 v41, 1.0, v36
	v_div_scale_f32 v36, s[8:9], v41, v41, v22
	v_rcp_f32_e32 v37, v36
	v_div_scale_f32 v38, vcc, v22, v41, v22
	v_fma_f32 v39, -v36, v37, 1.0
	v_fmac_f32_e32 v37, v39, v37
	v_mul_f32_e32 v39, v38, v37
	v_fma_f32 v40, -v36, v39, v38
	v_fmac_f32_e32 v39, v40, v37
	v_fma_f32 v36, -v36, v39, v38
	v_div_fmas_f32 v36, v36, v37, v39
	v_div_fixup_f32 v41, v36, v41, v22
	ds_write_b32 v3, v41 offset:12288
	s_waitcnt vmcnt(12)
	v_mul_f32_e32 v36, 0xbfb8aa3b, v23
	v_exp_f32_e32 v36, v36
	s_nop 0
	v_add_f32_e32 v41, 1.0, v36
	v_div_scale_f32 v36, s[8:9], v41, v41, v23
	v_rcp_f32_e32 v37, v36
	v_div_scale_f32 v38, vcc, v23, v41, v23
	v_fma_f32 v39, -v36, v37, 1.0
	v_fmac_f32_e32 v37, v39, v37
	v_mul_f32_e32 v39, v38, v37
	v_fma_f32 v40, -v36, v39, v38
	v_fmac_f32_e32 v39, v40, v37
	v_fma_f32 v36, -v36, v39, v38
	v_div_fmas_f32 v36, v36, v37, v39
	v_div_fixup_f32 v41, v36, v41, v23
	ds_write_b32 v3, v41 offset:14336
	s_waitcnt vmcnt(11)
	v_mul_f32_e32 v36, 0xbfb8aa3b, v24
	v_exp_f32_e32 v36, v36
	s_nop 0
	v_add_f32_e32 v41, 1.0, v36
	v_div_scale_f32 v36, s[8:9], v41, v41, v24
	v_rcp_f32_e32 v37, v36
	v_div_scale_f32 v38, vcc, v24, v41, v24
	v_fma_f32 v39, -v36, v37, 1.0
	v_fmac_f32_e32 v37, v39, v37
	v_mul_f32_e32 v39, v38, v37
	v_fma_f32 v40, -v36, v39, v38
	v_fmac_f32_e32 v39, v40, v37
	v_fma_f32 v36, -v36, v39, v38
	v_div_fmas_f32 v36, v36, v37, v39
	v_div_fixup_f32 v41, v36, v41, v24
	ds_write_b32 v3, v41 offset:16384
	s_waitcnt vmcnt(10)
	v_mul_f32_e32 v36, 0xbfb8aa3b, v25
	v_exp_f32_e32 v36, v36
	s_nop 0
	v_add_f32_e32 v41, 1.0, v36
	v_div_scale_f32 v36, s[8:9], v41, v41, v25
	v_rcp_f32_e32 v37, v36
	v_div_scale_f32 v38, vcc, v25, v41, v25
	v_fma_f32 v39, -v36, v37, 1.0
	v_fmac_f32_e32 v37, v39, v37
	v_mul_f32_e32 v39, v38, v37
	v_fma_f32 v40, -v36, v39, v38
	v_fmac_f32_e32 v39, v40, v37
	v_fma_f32 v36, -v36, v39, v38
	v_div_fmas_f32 v36, v36, v37, v39
	v_div_fixup_f32 v41, v36, v41, v25
	ds_write_b32 v3, v41 offset:18432
	s_waitcnt vmcnt(9)
	v_mul_f32_e32 v36, 0xbfb8aa3b, v26
	v_exp_f32_e32 v36, v36
	s_nop 0
	v_add_f32_e32 v41, 1.0, v36
	v_div_scale_f32 v36, s[8:9], v41, v41, v26
	v_rcp_f32_e32 v37, v36
	v_div_scale_f32 v38, vcc, v26, v41, v26
	v_fma_f32 v39, -v36, v37, 1.0
	v_fmac_f32_e32 v37, v39, v37
	v_mul_f32_e32 v39, v38, v37
	v_fma_f32 v40, -v36, v39, v38
	v_fmac_f32_e32 v39, v40, v37
	v_fma_f32 v36, -v36, v39, v38
	v_div_fmas_f32 v36, v36, v37, v39
	v_div_fixup_f32 v41, v36, v41, v26
	ds_write_b32 v3, v41 offset:20480
	s_waitcnt vmcnt(8)
	v_mul_f32_e32 v36, 0xbfb8aa3b, v27
	v_exp_f32_e32 v36, v36
	s_nop 0
	v_add_f32_e32 v41, 1.0, v36
	v_div_scale_f32 v36, s[8:9], v41, v41, v27
	v_rcp_f32_e32 v37, v36
	v_div_scale_f32 v38, vcc, v27, v41, v27
	v_fma_f32 v39, -v36, v37, 1.0
	v_fmac_f32_e32 v37, v39, v37
	v_mul_f32_e32 v39, v38, v37
	v_fma_f32 v40, -v36, v39, v38
	v_fmac_f32_e32 v39, v40, v37
	v_fma_f32 v36, -v36, v39, v38
	v_div_fmas_f32 v36, v36, v37, v39
	v_div_fixup_f32 v41, v36, v41, v27
	ds_write_b32 v3, v41 offset:22528
	s_waitcnt vmcnt(7)
	v_mul_f32_e32 v36, 0xbfb8aa3b, v28
	v_exp_f32_e32 v36, v36
	s_nop 0
	v_add_f32_e32 v41, 1.0, v36
	v_div_scale_f32 v36, s[8:9], v41, v41, v28
	v_rcp_f32_e32 v37, v36
	v_div_scale_f32 v38, vcc, v28, v41, v28
	v_fma_f32 v39, -v36, v37, 1.0
	v_fmac_f32_e32 v37, v39, v37
	v_mul_f32_e32 v39, v38, v37
	v_fma_f32 v40, -v36, v39, v38
	v_fmac_f32_e32 v39, v40, v37
	v_fma_f32 v36, -v36, v39, v38
	v_div_fmas_f32 v36, v36, v37, v39
	v_div_fixup_f32 v41, v36, v41, v28
	ds_write_b32 v3, v41 offset:24576
	s_waitcnt vmcnt(6)
; __device__ __forceinline__ void phase_p0a(const Args& a, LAS unsigned char* lds, int bid, int G, int wave) {
;     ...
;         for (int i = tid; i < NBATCH * D; i += NTHREADS) { const int b = i >> 10, k = i & 1023; const float c = b < 8 ? a.cp[b * D + k] : a.cs[(b - 8) * D + k]; sc[i] = c / (1.0f + __expf(-c)); }
	v_mul_f32_e32 v36, 0xbfb8aa3b, v29
	v_exp_f32_e32 v36, v36
	s_nop 0
	v_add_f32_e32 v41, 1.0, v36
	v_div_scale_f32 v36, s[8:9], v41, v41, v29
	v_rcp_f32_e32 v37, v36
	v_div_scale_f32 v38, vcc, v29, v41, v29
	v_fma_f32 v39, -v36, v37, 1.0
	v_fmac_f32_e32 v37, v39, v37
	v_mul_f32_e32 v39, v38, v37
	v_fma_f32 v40, -v36, v39, v38
	v_fmac_f32_e32 v39, v40, v37
	v_fma_f32 v36, -v36, v39, v38
	v_div_fmas_f32 v36, v36, v37, v39
	v_div_fixup_f32 v41, v36, v41, v29
	ds_write_b32 v3, v41 offset:26624
	s_waitcnt vmcnt(5)
	v_mul_f32_e32 v36, 0xbfb8aa3b, v30
	v_exp_f32_e32 v36, v36
	s_nop 0
	v_add_f32_e32 v41, 1.0, v36
	v_div_scale_f32 v36, s[8:9], v41, v41, v30
	v_rcp_f32_e32 v37, v36
	v_div_scale_f32 v38, vcc, v30, v41, v30
	v_fma_f32 v39, -v36, v37, 1.0
	v_fmac_f32_e32 v37, v39, v37
	v_mul_f32_e32 v39, v38, v37
	v_fma_f32 v40, -v36, v39, v38
	v_fmac_f32_e32 v39, v40, v37
	v_fma_f32 v36, -v36, v39, v38
	v_div_fmas_f32 v36, v36, v37, v39
	v_div_fixup_f32 v41, v36, v41, v30
	ds_write_b32 v3, v41 offset:28672
	s_waitcnt vmcnt(4)
	v_mul_f32_e32 v36, 0xbfb8aa3b, v31
	v_exp_f32_e32 v36, v36
	s_nop 0
	v_add_f32_e32 v41, 1.0, v36
	v_div_scale_f32 v36, s[8:9], v41, v41, v31
	v_rcp_f32_e32 v37, v36
	v_div_scale_f32 v38, vcc, v31, v41, v31
	v_fma_f32 v39, -v36, v37, 1.0
	v_fmac_f32_e32 v37, v39, v37
	v_mul_f32_e32 v39, v38, v37
	v_fma_f32 v40, -v36, v39, v38
	v_fmac_f32_e32 v39, v40, v37
	v_fma_f32 v36, -v36, v39, v38
	v_div_fmas_f32 v36, v36, v37, v39
	v_div_fixup_f32 v41, v36, v41, v31
	ds_write_b32 v3, v41 offset:30720
	s_waitcnt vmcnt(3)
	v_mul_f32_e32 v36, 0xbfb8aa3b, v32
	v_exp_f32_e32 v36, v36
	s_nop 0
	v_add_f32_e32 v41, 1.0, v36
	v_div_scale_f32 v36, s[8:9], v41, v41, v32
	v_rcp_f32_e32 v37, v36
	v_div_scale_f32 v38, vcc, v32, v41, v32
	v_fma_f32 v39, -v36, v37, 1.0
	v_fmac_f32_e32 v37, v39, v37
	v_mul_f32_e32 v39, v38, v37
	v_fma_f32 v40, -v36, v39, v38
	v_fmac_f32_e32 v39, v40, v37
	v_fma_f32 v36, -v36, v39, v38
	v_div_fmas_f32 v36, v36, v37, v39
	v_div_fixup_f32 v41, v36, v41, v32
	ds_write_b32 v3, v41 offset:32768
	s_waitcnt vmcnt(2)
	v_mul_f32_e32 v36, 0xbfb8aa3b, v33
	v_exp_f32_e32 v36, v36
	s_nop 0
	v_add_f32_e32 v41, 1.0, v36
	v_div_scale_f32 v36, s[8:9], v41, v41, v33
	v_rcp_f32_e32 v37, v36
	v_div_scale_f32 v38, vcc, v33, v41, v33
	v_fma_f32 v39, -v36, v37, 1.0
	v_fmac_f32_e32 v37, v39, v37
	v_mul_f32_e32 v39, v38, v37
	v_fma_f32 v40, -v36, v39, v38
	v_fmac_f32_e32 v39, v40, v37
	v_fma_f32 v36, -v36, v39, v38
	v_div_fmas_f32 v36, v36, v37, v39
	v_div_fixup_f32 v41, v36, v41, v33
	ds_write_b32 v3, v41 offset:34816
	s_waitcnt vmcnt(1)
	v_mul_f32_e32 v36, 0xbfb8aa3b, v34
	v_exp_f32_e32 v36, v36
	s_nop 0
	v_add_f32_e32 v41, 1.0, v36
	v_div_scale_f32 v36, s[8:9], v41, v41, v34
	v_rcp_f32_e32 v37, v36
	v_div_scale_f32 v38, vcc, v34, v41, v34
	v_fma_f32 v39, -v36, v37, 1.0
	v_fmac_f32_e32 v37, v39, v37
	v_mul_f32_e32 v39, v38, v37
	v_fma_f32 v40, -v36, v39, v38
	v_fmac_f32_e32 v39, v40, v37
	v_fma_f32 v36, -v36, v39, v38
	v_div_fmas_f32 v36, v36, v37, v39
	v_div_fixup_f32 v41, v36, v41, v34
	ds_write_b32 v3, v41 offset:36864
	s_waitcnt vmcnt(0)
	v_mul_f32_e32 v36, 0xbfb8aa3b, v35
	v_exp_f32_e32 v36, v36
	s_nop 0
	v_add_f32_e32 v41, 1.0, v36
	v_div_scale_f32 v36, s[8:9], v41, v41, v35
	v_rcp_f32_e32 v37, v36
	v_div_scale_f32 v38, vcc, v35, v41, v35
	v_fma_f32 v39, -v36, v37, 1.0
	v_fmac_f32_e32 v37, v39, v37
	v_mul_f32_e32 v39, v38, v37
	v_fma_f32 v40, -v36, v39, v38
	v_fmac_f32_e32 v39, v40, v37
	v_fma_f32 v36, -v36, v39, v38
	v_div_fmas_f32 v36, v36, v37, v39
	v_div_fixup_f32 v41, v36, v41, v35
	ds_write_b32 v3, v41 offset:38912

; __global__ void __launch_bounds__(NTHREADS, 2) fwd_megakernel(Args a) {
;     ...
;     if (ph0 == 0 && a.ph_hi > 1) { phase_p0a(a, lds, bid, G, wave); cg::this_grid().sync(); ph0 = 1; }
;     ...
;     for (int ph = ph0; ph < a.ph_hi; ++ph) {
;     ...
;             const float* mod_l = (const float*)(ws + WS_MOD) + (size_t)l * NBATCH * NMOD;
;             const float* gmt = (const float*)(ws + WS_GM);
;             const float* svl = (const float*)(ws + WS_SV) + (size_t)l * SV_LAYER;
;             float* rss = (float*)(ws + WS_RSS);
;             bf16_t* xg = (bf16_t*)(ws + WS_XG);
;             bf16_t* zh = (bf16_t*)(ws + WS_ZH);
.LBB0_70:
	s_or_b64 exec, exec, s[0:1]
	v_lshrrev_b32_e32 v2, 20, v0
	v_lshrrev_b32_e32 v0, 10, v0
	v_or_b32_e32 v0, v0, v2
	s_movk_i32 s0, 0x3ff
	v_and_or_b32 v0, v0, s0, v1
	v_cmp_eq_u32_e32 vcc, 0, v0
	s_barrier
	s_mov_b32 s86, 0
.LBB0_81:
	s_cmp_ge_i32 s86, s87
	s_cbranch_scc1 .LBB0_639
	v_readlane_b32 s37, v251, 0
	s_lshl_b32 s0, s37, 3
	s_add_i32 s38, s14, s0
	s_lshl_b32 s92, s3, 3
	s_cmp_lt_i32 s38, 0x10000
	s_cselect_b64 s[0:1], -1, 0
	v_writelane_b32 v251, s0, 35
	s_add_u32 s96, s84, 0x500000
	s_addc_u32 s97, s85, 0
	v_writelane_b32 v251, s1, 36
	s_and_b32 s0, s19, 0xffffffc0
	s_add_u32 s12, s84, 0x100000
	s_addc_u32 s13, s85, 0
	s_add_u32 s4, s84, 0x200000
	s_addc_u32 s5, s85, 0
	v_writelane_b32 v251, s4, 37
	s_lshl_b32 s1, s37, 9
	v_mov_b32_e32 v0, 0x4200
	v_writelane_b32 v251, s5, 38
	v_writelane_b32 v251, s0, 39
	s_add_i32 s0, s0, s1
	s_lshl_b32 s4, s3, 9
	v_writelane_b32 v251, s1, 40
	s_cmpk_lt_i32 s38, 0x6c0
	v_writelane_b32 v251, s0, 41
	s_cselect_b64 s[0:1], -1, 0
	s_add_u32 s95, s84, 0xe00000
	s_addc_u32 s15, s85, 0
	s_add_u32 s18, s84, 0x5000000
	v_writelane_b32 v251, s0, 42
	s_addc_u32 s17, s85, 0
	v_sub_co_u32_e32 v0, vcc, s38, v0
	v_writelane_b32 v251, s1, 43
	s_add_u32 s0, s84, 0x300000
	v_writelane_b32 v251, s0, 44
	s_addc_u32 s0, s85, 0
	v_writelane_b32 v251, s0, 45
	s_add_u32 s8, s84, 0x5e00000
	s_mul_i32 s0, s14, 0x2800
	s_addc_u32 s9, s85, 0
	s_add_i32 s0, s0, 0
	s_cmpk_lt_i32 s37, 0x120
	v_writelane_b32 v251, s0, 46
	s_cselect_b64 s[0:1], -1, 0
	v_writelane_b32 v251, s0, 47
	v_mov_b32_e32 v1, 0x4c00
	s_mov_b32 s11, 0
	v_writelane_b32 v251, s1, 48
	s_lshl_b32 s0, s14, 7
	s_cmpk_lt_i32 s38, 0x5000
	s_cselect_b64 s[6:7], -1, 0
	v_writelane_b32 v251, s6, 49
	s_cmpk_gt_i32 s38, 0x2bff
	s_mul_hi_u32 s0, s0, 0x9000
	v_writelane_b32 v251, s7, 50
	s_cselect_b64 s[6:7], -1, 0
	v_writelane_b32 v251, s6, 51
	v_mov_b32_e32 v193, 0
	v_mov_b32_e32 v194, 0x358637bd
	v_writelane_b32 v251, s7, 52
	s_xor_b64 s[6:7], vcc, -1
	v_writelane_b32 v251, s6, 53
	v_sub_co_u32_e32 v1, vcc, s38, v1
	s_nop 0
	v_writelane_b32 v251, s7, 54
	v_readfirstlane_b32 s1, v1
	s_lshr_b32 s10, s1, 9
	v_readlane_b32 s64, v251, 3
	s_lshl_b64 s[6:7], s[10:11], 22
	v_readlane_b32 s72, v251, 11
	v_readlane_b32 s73, v251, 12
	v_readlane_b32 s78, v251, 17
	v_readlane_b32 s79, v251, 18
	s_mov_b64 s[72:73], s[12:13]
	s_add_u32 s12, s78, s6
	s_addc_u32 s22, s79, s7
	s_add_u32 s1, s84, 0x5a00000
	s_addc_u32 s2, s85, 0
	s_lshl_b64 s[6:7], s[10:11], 21
	s_add_u32 s10, s1, s6
	v_readlane_b32 s65, v251, 4
	v_readlane_b32 s66, v251, 5
	v_readlane_b32 s67, v251, 6
	v_readlane_b32 s68, v251, 7
	v_readlane_b32 s69, v251, 8
	v_readlane_b32 s70, v251, 9
	v_readlane_b32 s71, v251, 10
	v_readlane_b32 s74, v251, 13
	v_readlane_b32 s75, v251, 14
	v_readlane_b32 s76, v251, 15
	v_readlane_b32 s77, v251, 16
	v_writelane_b32 v251, s1, 55
	s_addc_u32 s23, s2, s7
	s_and_b32 s26, s38, 0x1ff
	v_readfirstlane_b32 s1, v0
	s_cmpk_gt_u32 s1, 0x4ff
	v_writelane_b32 v251, s2, 56
	s_cselect_b32 s2, 0xa00000, 0
	s_cselect_b32 s5, 0x500000, 0
	s_add_u32 s27, s66, s2
	s_addc_u32 s28, s67, 0
	s_add_u32 s29, s18, s5
	s_addc_u32 s33, s17, 0
	s_add_i32 s2, s38, 0xffffb900
	s_cmpk_lt_u32 s1, 0x500
	s_cselect_b32 s34, s1, s2
	s_add_i32 s1, s38, 0xd400
	s_and_b32 s2, s1, 0xffff
	s_mul_i32 s2, s2, 0xba2f
	s_lshr_b32 s2, s2, 26
	s_mul_i32 s5, s2, 0xb00000
	v_writelane_b32 v251, s18, 57
	s_add_u32 s6, s64, s5
	v_writelane_b32 v251, s17, 58
	s_addc_u32 s7, s65, 0
	v_writelane_b32 v251, s6, 59
	s_mul_i32 s5, s2, 0x580000
	s_mulk_i32 s2, 0x580
	v_writelane_b32 v251, s7, 60
	s_add_u32 s6, s84, 0x3a00000
	s_addc_u32 s7, s85, 0
	v_writelane_b32 v251, s6, 61
	s_add_u32 s6, s6, s5
	v_writelane_b32 v251, s7, 62
	s_addc_u32 s7, s7, 0
	s_sub_i32 s1, s1, s2
	s_mul_hi_i32 s2, s38, 0x2e8ba2e9
	s_lshr_b32 s5, s2, 31
	s_ashr_i32 s2, s2, 9
	s_add_i32 s2, s2, s5
	v_writelane_b32 v251, s6, 63
	s_and_b32 s1, s1, 0xffff
	s_mul_i32 s5, s2, 0x1600000
	v_writelane_b32 v252, s7, 0
	v_writelane_b32 v252, s1, 1
	s_mul_hi_i32 s1, s2, 0x1600000
	s_add_u32 s6, s54, s5
	s_addc_u32 s7, s55, s1
	v_writelane_b32 v252, s6, 2
	s_mul_i32 s5, s2, 0xb00000
	s_mul_hi_i32 s1, s2, 0xb00000
	v_writelane_b32 v252, s7, 3
	s_add_u32 s6, s95, s5
	v_writelane_b32 v252, s15, 4
	s_addc_u32 s7, s15, s1
	s_mulk_i32 s2, 0xb00
	v_writelane_b32 v252, s6, 5
	s_sub_i32 s1, s38, s2
	v_mbcnt_lo_u32_b32 v0, -1, 0
	v_writelane_b32 v252, s7, 6
	s_add_u32 s6, s84, 0xd00000
	v_writelane_b32 v252, s1, 7
	s_addc_u32 s7, s85, 0
	v_writelane_b32 v252, s6, 8
	s_add_u32 s30, s84, 0xde00000
	s_addc_u32 s31, s85, 0
	v_writelane_b32 v252, s7, 9
	s_lshl_b32 s1, s14, 3
	s_bfe_u32 s17, s19, 0x20006
	v_writelane_b32 v252, s1, 10
	s_lshr_b32 s1, s19, 8
	s_cmpk_lt_i32 s37, 0x400
	s_cselect_b64 s[6:7], -1, 0
	s_ashr_i32 s58, s37, 31
	s_lshr_b32 s2, s58, 29
	s_add_i32 s5, s37, s2
	s_ashr_i32 s2, s5, 3
	s_and_b32 s5, s5, -8
	s_sub_i32 s5, s37, s5
	s_lshl_b32 s35, s5, 7
	v_writelane_b32 v252, s6, 11
	s_cmp_eq_u32 s1, 1
	v_mbcnt_hi_u32_b32 v234, -1, v0
	v_writelane_b32 v252, s7, 12
	s_cselect_b64 s[6:7], -1, 0
	s_cmpk_lt_u32 s19, 0x100
	v_writelane_b32 v252, s6, 13
	s_cselect_b64 s[20:21], -1, 0
	s_lshl_b32 s91, s1, 6
	s_lshl_b32 s15, s17, 5
	s_ashr_i32 s13, s3, 31
	v_writelane_b32 v252, s7, 14
	s_add_u32 s6, s84, 0x900000
	s_addc_u32 s7, s85, 0
	v_writelane_b32 v252, s6, 15
	s_cmpk_lt_i32 s37, 0xa00
	v_and_b32_e32 v0, 64, v234
	v_writelane_b32 v252, s7, 16
	s_cselect_b64 s[6:7], -1, 0
	s_lshl_b32 s18, s14, 10
	v_writelane_b32 v252, s6, 17
	s_cmp_lt_u32 s19, 64
	s_cselect_b64 s[24:25], -1, 0
	v_writelane_b32 v252, s7, 18
	s_lshl_b32 s6, s17, 1
	s_orn2_b32 s6, s6, 63
	v_writelane_b32 v252, s6, 19
; __device__ __forceinline__ int lane_id_v() { int l; asm volatile("v_mbcnt_lo_u32_b32 %0, -1, 0\n\tv_mbcnt_hi_u32_b32 %0, -1, %0" : "=v"(l)); return l; }
; __device__ __forceinline__ unsigned xb_ld(unsigned* p)              { return __hip_atomic_load(p, __ATOMIC_RELAXED, __HIP_MEMORY_SCOPE_AGENT); }
; __device__ __forceinline__ unsigned xb_add(unsigned* p, unsigned v) { return __hip_atomic_fetch_add(p, v, __ATOMIC_RELAXED, __HIP_MEMORY_SCOPE_AGENT); }
; #define XB_SPIN(cond, bar) do { unsigned _sp = 0; while (cond) { __builtin_amdgcn_s_sleep(1); \
;     if ((++_sp & 255u) == 0u) { if (xb_ld(&(bar)[XB_TMO])) break; if (_sp > XB_SPIN_CAP) { atomicAdd(&(bar)[XB_TMO], 1u); break; } } } } while (0)
; __device__ __forceinline__ void xcd_barrier_complete(unsigned* bar, unsigned x, unsigned& nloc, unsigned& nx) {
;     ...
;         for (unsigned j = 0; j < 16; ++j) { const unsigned c = xb_ld(&bar[XB_XCNT(j)]); sum += c; cnt += (c > 0u) ? 1u : 0u; mine = (j == x) ? c : mine; }
;         if (sum == G) break;
;         __builtin_amdgcn_s_sleep(1);
;         if ((++sp & 255u) == 0u) { if (xb_ld(&bar[XB_TMO])) break; if (sp > XB_SPIN_CAP) { atomicAdd(&bar[XB_TMO], 1u); break; } }
;     }
;     nloc = mine > 0u ? mine : 1u; nx = cnt > 0u ? cnt : 1u;
; }
; __device__ __forceinline__ void xcd_barrier(const XcdBarrier& b, int wave) {
;     asm volatile("s_waitcnt vmcnt(0)" ::: "memory");
;     __syncthreads();
;     if (wave == 0 && pg8::lane_id_v() == 0) {
;         unsigned* bar = b.bar;
;         __builtin_amdgcn_s_waitcnt(0);
;         unsigned nloc = b.st[0], nx = b.st[1];
;         if (nloc == 0u) { xcd_barrier_complete(bar, b.x, nloc, nx); b.st[0] = nloc; b.st[1] = nx; }
;         const unsigned old = xb_add(&bar[XB_XSUB(b.x)], 1u);
;         const unsigned gen = old / nloc;
;         if (old + 1u == (gen + 1u) * nloc) {
;             __builtin_amdgcn_fence(__ATOMIC_RELEASE, "agent");
;             asm volatile("s_waitcnt vmcnt(0)" ::: "memory");
;             const unsigned og = xb_add(&bar[XB_TOP], 1u);
;             const unsigned tg = og / nx;
;             if (og + 1u == (tg + 1u) * nx) xb_add(&bar[XB_TOPGEN], 1u);
;             else XB_SPIN(xb_ld(&bar[XB_TOPGEN]) == tg, bar);
;             __builtin_amdgcn_fence(__ATOMIC_ACQUIRE, "agent");
;             xb_add(&bar[XB_XGEN(b.x)], 1u);
	s_add_i32 s6, s18, 0x2000
	s_ashr_i32 s7, s6, 31
	v_writelane_b32 v252, s6, 20
	s_ashr_i32 s19, s18, 31
	v_mov_b32_e32 v196, 1.0
	v_writelane_b32 v252, s7, 21
	s_lshl_b32 s6, s17, 7
	s_add_i32 s6, s6, 0
	s_add_i32 s6, s6, 0x26400
	s_cmpk_lt_i32 s37, 0x200
	v_writelane_b32 v252, s6, 22
	s_cselect_b64 s[6:7], -1, 0
	v_writelane_b32 v252, s6, 23
	s_lshl_b32 s40, s14, 4
	v_mov_b32_e32 v195, 1
	v_writelane_b32 v252, s7, 24
	s_add_u32 s6, s84, 0x21e000
	v_writelane_b32 v252, s6, 25
	s_addc_u32 s6, s85, 0
	s_lshl_b32 s36, s5, 6
	s_cmpk_lt_i32 s37, 0xb00
	v_writelane_b32 v252, s6, 26
	s_cselect_b64 s[6:7], -1, 0
	v_writelane_b32 v252, s6, 27
	v_add_u32_e32 v236, 64, v0
	v_xor_b32_e32 v237, 2, v234
	v_writelane_b32 v252, s7, 28
	s_add_u32 s6, s84, 0x200
	s_addc_u32 s7, s85, 0
	v_writelane_b32 v252, s6, 29
	v_xor_b32_e32 v250, 4, v234
	v_xor_b32_e32 v235, 8, v234
	v_writelane_b32 v252, s7, 30
	s_add_u32 s6, s84, 0x1000
	s_addc_u32 s7, s85, 0
	v_writelane_b32 v252, s6, 31
	v_mov_b64_e32 v[238:239], 0x1ff
	v_mov_b64_e32 v[202:203], 0xaff
	v_writelane_b32 v252, s7, 32
	s_add_u32 s6, s84, 0x1100
	s_addc_u32 s7, s85, 0
	v_writelane_b32 v252, s6, 33
	v_mov_b32_e32 v240, 0x5800
	v_mov_b64_e32 v[204:205], 0xa00
	v_writelane_b32 v252, s7, 34
	s_add_u32 s6, s84, 0x1200
	s_addc_u32 s7, s85, 0
	v_writelane_b32 v252, s6, 35
	v_mov_b64_e32 v[206:207], 0x9ff
	s_mov_b32 s65, 0x9000
	v_writelane_b32 v252, s7, 36
	s_add_u32 s6, s84, 0x1300
	s_addc_u32 s7, s85, 0
	v_writelane_b32 v252, s6, 37
	s_cmp_eq_u32 s16, 15
	s_mov_b32 s67, 0x800000
	v_writelane_b32 v252, s7, 38
	s_cselect_b64 s[6:7], -1, 0
	v_writelane_b32 v252, s6, 39
	s_cmp_eq_u32 s16, 14
	s_movk_i32 s94, 0x7fff
	v_writelane_b32 v252, s7, 40
	s_cselect_b64 s[6:7], -1, 0
	v_writelane_b32 v252, s6, 41
	s_cmp_eq_u32 s16, 13
	s_mov_b64 s[60:61], 0x8000
	v_writelane_b32 v252, s7, 42
	s_cselect_b64 s[6:7], -1, 0
	v_writelane_b32 v252, s6, 43
	s_cmp_eq_u32 s16, 12
	s_mov_b32 s88, 0xbfb8aa3b
	v_writelane_b32 v252, s7, 44
	s_cselect_b64 s[6:7], -1, 0
	v_writelane_b32 v252, s6, 45
	s_cmp_eq_u32 s16, 11
	s_mov_b32 s90, 0x3f07dc22
	v_writelane_b32 v252, s7, 46
	s_cselect_b64 s[6:7], -1, 0
	v_writelane_b32 v252, s6, 47
	s_cmp_eq_u32 s16, 10
	s_mov_b32 s64, 0x3e027906
	v_writelane_b32 v252, s7, 48
	s_cselect_b64 s[6:7], -1, 0
	v_writelane_b32 v252, s6, 49
	s_cmp_eq_u32 s16, 9
	s_mov_b32 s66, 0xbf38aa3b
	v_writelane_b32 v252, s7, 50
	s_cselect_b64 s[6:7], -1, 0
	v_writelane_b32 v252, s6, 51
	s_cmp_eq_u32 s16, 8
	s_nop 0
	v_writelane_b32 v252, s7, 52
	s_cselect_b64 s[6:7], -1, 0
	v_writelane_b32 v252, s6, 53
	s_cmp_eq_u32 s16, 7
	s_nop 0
	v_writelane_b32 v252, s7, 54
	s_cselect_b64 s[6:7], -1, 0
	v_writelane_b32 v252, s6, 55
	s_cmp_eq_u32 s16, 6
	s_nop 0
	v_writelane_b32 v252, s7, 56
	s_cselect_b64 s[6:7], -1, 0
	v_writelane_b32 v252, s6, 57
	s_cmp_eq_u32 s16, 5
	s_nop 0
	v_writelane_b32 v252, s7, 58
	s_cselect_b64 s[6:7], -1, 0
	v_writelane_b32 v252, s6, 59
	s_cmp_eq_u32 s16, 4
	s_nop 0
	v_writelane_b32 v252, s7, 60
	s_cselect_b64 s[6:7], -1, 0
	v_writelane_b32 v252, s6, 61
	s_cmp_eq_u32 s16, 3
	s_nop 0
	v_writelane_b32 v252, s7, 62
	s_cselect_b64 s[6:7], -1, 0
	v_writelane_b32 v252, s6, 63
	s_cmp_eq_u32 s16, 2
	s_nop 0
	v_writelane_b32 v253, s7, 0
	s_cselect_b64 s[6:7], -1, 0
	v_writelane_b32 v253, s6, 1
	s_cmp_eq_u32 s16, 1
	s_nop 0
	v_writelane_b32 v253, s7, 2
	s_cselect_b64 s[6:7], -1, 0
	v_writelane_b32 v253, s6, 3
	s_cmp_eq_u32 s16, 0
	s_nop 0
	v_writelane_b32 v253, s7, 4
	s_cselect_b64 s[6:7], -1, 0
	v_writelane_b32 v253, s6, 5
	s_nop 1
	v_writelane_b32 v253, s7, 6
	s_lshl_b32 s6, s16, 8
	s_add_u32 s6, s84, s6
	s_addc_u32 s7, s85, 0
	s_add_u32 s42, s6, 0x1400
	s_addc_u32 s43, s7, 0
	v_writelane_b32 v253, s42, 7
	s_add_u32 s6, s6, 0x2400
	s_addc_u32 s7, s7, 0
	v_writelane_b32 v253, s43, 8
	v_writelane_b32 v253, s6, 9
	s_nop 1
	v_writelane_b32 v253, s7, 10
	s_add_u32 s6, s84, 0x3400
	s_addc_u32 s7, s85, 0
	v_writelane_b32 v253, s6, 11
	s_nop 1
	v_writelane_b32 v253, s7, 12
	s_add_u32 s6, s84, 0x3500
	s_addc_u32 s7, s85, 0
	v_writelane_b32 v253, s6, 13
	s_nop 1
	v_writelane_b32 v253, s7, 14
	s_and_b64 s[6:7], vcc, exec
	s_cselect_b32 s6, s27, s12
	s_cselect_b32 s7, s28, s22
	v_writelane_b32 v253, s6, 15
	s_movk_i32 s12, 0x161
	s_nop 0
	v_writelane_b32 v253, s7, 16
	s_cselect_b32 s6, s29, s10
	s_cselect_b32 s7, s33, s23
	v_writelane_b32 v253, s6, 17
	s_movk_i32 s10, 0x141
	s_mul_i32 s33, s14, 0x440
	v_writelane_b32 v253, s7, 18
	s_cselect_b32 s6, s34, s26
	v_writelane_b32 v253, s6, 19
	s_movk_i32 s6, 0xa00
	s_cselect_b32 s6, s6, 0x400
	v_writelane_b32 v253, s6, 20
	s_cselect_b32 s6, 2, 0
	v_writelane_b32 v253, s6, 21
	s_cmp_lt_i32 s5, 0
	s_mul_i32 s6, s5, 0x81
	s_cselect_b32 s6, s6, s35
	s_mul_i32 s7, s5, 0x41
	s_cselect_b32 s7, s7, s36
	s_cselect_b32 s10, s10, 0x140
	s_cselect_b32 s12, s12, 0x160
	s_add_i32 s6, s6, s2
	s_ashr_i32 s16, s6, 31
	s_lshr_b32 s16, s16, 27
	s_add_i32 s16, s6, s16
	s_and_b32 s22, s16, 0xffe0
	s_sub_i32 s6, s6, s22
	s_bfe_i32 s22, s6, 0x80000
	s_bfe_u32 s22, s22, 0x3000c
	s_add_i32 s22, s6, s22
	s_mul_i32 s10, s5, s10
	s_and_b32 s23, s22, 0xf8
	s_add_i32 s10, s10, s2
	s_sub_i32 s6, s6, s23
	s_mul_hi_i32 s23, s10, 0x66666667
	s_lshr_b32 s26, s23, 31
	s_ashr_i32 s23, s23, 5
	s_add_i32 s23, s23, s26
	s_mul_i32 s26, s23, 0x50
	s_sub_i32 s10, s10, s26
	s_bfe_i32 s26, s10, 0x80000
	s_bfe_u32 s26, s26, 0x3000c
	s_add_i32 s26, s10, s26
	s_and_b32 s27, s26, 0xf8
	s_add_i32 s7, s7, s2
	s_sub_i32 s10, s10, s27
	s_ashr_i32 s27, s7, 31
	s_lshr_b32 s27, s27, 27
	s_add_i32 s27, s7, s27
; #define GRID_SYNC(first) do { xcd_barrier(xbar, wave); } while (0)
; __global__ void __launch_bounds__(NTHREADS, 2) fwd_megakernel(Args a) {
;     ...
;     if (ph0 == 0 && a.ph_hi > 1) { phase_p0a(a, lds, bid, G, wave); cg::this_grid().sync(); ph0 = 1; }
;     ...
;     for (int ph = ph0; ph < a.ph_hi; ++ph) {
;     ...
;         if (ph + 1 < a.ph_hi) GRID_SYNC(ph == a.ph_lo);
	s_and_b32 s28, s27, 0xffe0
	s_sub_i32 s7, s7, s28
	s_bfe_i32 s28, s7, 0x80000
	s_bfe_u32 s28, s28, 0x3000c
	s_add_i32 s28, s7, s28
	s_and_b32 s29, s28, 0xf8
	s_mul_i32 s5, s5, s12
	s_sub_i32 s7, s7, s29
	s_ashr_i32 s27, s27, 5
	s_add_i32 s5, s5, s2
	s_lshl_b32 s27, s27, 3
	s_sext_i32_i8 s7, s7
	s_mul_hi_i32 s2, s5, 0x2e8ba2e9
	s_add_i32 s27, s27, s7
	s_lshr_b32 s7, s2, 31
	s_ashr_i32 s2, s2, 5
	s_add_i32 s2, s2, s7
	s_mul_i32 s7, s2, 0xb0
	s_sub_i32 s5, s5, s7
	s_bfe_u32 s7, s5, 0x3001c
	s_add_i32 s7, s5, s7
	s_and_b32 s12, s7, 0xfff8
	s_sub_i32 s5, s5, s12
	s_ashr_i32 s12, s16, 5
	s_lshl_b32 s12, s12, 3
	s_sext_i32_i8 s6, s6
	s_bfe_i32 s16, s22, 0x80000
	s_add_i32 s22, s12, s6
	s_lshl_b32 s6, s23, 3
	s_sext_i32_i8 s10, s10
	s_add_i32 s34, s6, s10
	s_bfe_i32 s6, s28, 0x80000
	s_sext_i32_i16 s6, s6
	s_ashr_i32 s6, s6, 3
	v_writelane_b32 v253, s6, 22
	s_lshl_b32 s2, s2, 3
	s_sext_i32_i16 s6, s7
	s_sext_i32_i16 s5, s5
	s_add_i32 s28, s2, s5
	s_ashr_i32 s2, s6, 3
	v_writelane_b32 v253, s2, 23
	s_lshr_b32 s2, s6, 3
	s_bfe_i64 s[6:7], s[2:3], 0x100000
	s_lshl_b64 s[6:7], s[6:7], 19
	s_sext_i32_i16 s16, s16
	v_writelane_b32 v253, s6, 24
	s_ashr_i32 s2, s16, 3
	s_bfe_i32 s12, s26, 0x80000
	v_writelane_b32 v253, s7, 25
	v_writelane_b32 v253, s2, 26
	s_lshr_b32 s2, s16, 3
	s_bfe_i64 s[6:7], s[2:3], 0x100000
	s_lshl_b64 s[6:7], s[6:7], 19
	s_sext_i32_i16 s12, s12
	v_writelane_b32 v253, s6, 27
	s_ashr_i32 s2, s12, 3
	s_ashr_i32 s29, s28, 31
	v_writelane_b32 v253, s7, 28
	v_writelane_b32 v253, s2, 29
	s_mov_b32 s6, s28
	v_writelane_b32 v253, s6, 30
	s_ashr_i32 s23, s22, 31
	s_lshr_b32 s2, s12, 3
	v_writelane_b32 v253, s7, 31
	s_lshl_b64 s[6:7], s[28:29], 19
	v_writelane_b32 v253, s6, 32
	s_mul_i32 s5, s27, 0x160000
	s_mov_b32 s16, 0x3a800000
	v_writelane_b32 v253, s7, 33
	s_mov_b32 s6, s22
	v_writelane_b32 v253, s6, 34
	s_mov_b32 s12, 0x3e6d3388
	s_mov_b32 s28, 0x3f35f0e3
	v_writelane_b32 v253, s7, 35
	s_lshl_b64 s[6:7], s[22:23], 20
	s_add_u32 s6, s30, s6
	s_addc_u32 s7, s31, s7
	s_add_u32 s22, s6, 0x80000
	v_writelane_b32 v253, s6, 36
	s_addc_u32 s23, s7, 0
	s_ashr_i32 s35, s34, 31
	v_writelane_b32 v253, s7, 37
	v_writelane_b32 v253, s22, 38
	s_bfe_i64 s[6:7], s[2:3], 0x100000
	s_lshl_b64 s[6:7], s[6:7], 19
	v_writelane_b32 v253, s23, 39
	v_writelane_b32 v253, s6, 40
	s_mov_b32 s2, s34
	s_nop 0
	v_writelane_b32 v253, s7, 41
	s_lshl_b64 s[6:7], s[34:35], 19
	v_writelane_b32 v253, s2, 42
	s_add_u32 s6, s8, s6
	s_addc_u32 s7, s9, s7
	v_writelane_b32 v253, s3, 43
	s_add_u32 s22, s6, 0x40000
	v_writelane_b32 v253, s6, 44
	s_addc_u32 s23, s7, 0
	s_mul_hi_i32 s2, s27, 0x160000
	v_writelane_b32 v253, s7, 45
	v_writelane_b32 v253, s22, 46
	s_add_u32 s6, s30, s5
	s_addc_u32 s7, s31, s2
	v_writelane_b32 v253, s23, 47
	v_writelane_b32 v253, s27, 48
	s_add_u32 s22, s6, 0xb0000
	v_writelane_b32 v253, s6, 49
	s_addc_u32 s23, s7, 0
	s_ashr_i32 s39, s38, 31
	v_writelane_b32 v253, s7, 50
	s_lshl_b64 s[6:7], s[38:39], 6
	v_writelane_b32 v253, s22, 51
	s_add_u32 s6, s6, 0x500000
	s_addc_u32 s7, s7, 0
	v_writelane_b32 v253, s23, 52
	s_add_u32 s22, s84, s6
	v_writelane_b32 v253, s6, 53
	s_addc_u32 s23, s85, s7
	s_ashr_i32 s93, s92, 31
	v_writelane_b32 v253, s7, 54
	v_writelane_b32 v253, s22, 55
	s_lshl_b64 s[6:7], s[92:93], 6
	s_nop 0
	v_writelane_b32 v253, s23, 56
	v_writelane_b32 v253, s6, 57
	s_nop 1
	v_writelane_b32 v253, s7, 58
	s_lshl_b64 s[6:7], s[38:39], 12
	s_add_u32 s2, s82, s6
	s_addc_u32 s5, s83, s7
	s_add_u32 s6, s2, 0xc00
	s_addc_u32 s7, s5, 0
	v_writelane_b32 v253, s6, 59
	s_ashr_i32 s5, s4, 31
	s_nop 0
	v_writelane_b32 v253, s7, 60
	s_lshl_b64 s[6:7], s[92:93], 12
	v_writelane_b32 v253, s6, 61
	s_nop 1
	v_writelane_b32 v253, s7, 62
	s_lshl_b64 s[6:7], s[4:5], 2
	v_writelane_b32 v253, s6, 63
	s_nop 1
	v_writelane_b32 v254, s7, 0
	s_add_u32 s6, s84, 0x100200
	s_addc_u32 s7, s85, 0
	v_writelane_b32 v254, s6, 1
	s_lshl_b32 s2, s14, 8
	s_add_i32 s2, s2, 0
	v_writelane_b32 v254, s7, 2
	v_writelane_b32 v254, s2, 3
	v_writelane_b32 v254, s38, 4
	s_lshl_b64 s[6:7], s[38:39], 11
	s_mul_i32 s2, s14, 0x480000
	v_writelane_b32 v254, s39, 5
	v_writelane_b32 v254, s6, 6
	s_nop 1
	v_writelane_b32 v254, s7, 7
	s_lshl_b64 s[6:7], s[92:93], 11
	v_writelane_b32 v254, s6, 8
	s_nop 1
	v_writelane_b32 v254, s7, 9
	s_add_u32 s6, s48, s2
	s_addc_u32 s7, s49, s0
	v_writelane_b32 v254, s6, 10
	s_mul_i32 s0, s1, 0x2200
	s_lshl_b32 s1, s14, 14
	v_writelane_b32 v254, s7, 11
	v_writelane_b32 v254, s0, 12
	s_lshl_b32 s0, s14, 9
	s_add_i32 s29, s0, 0
	s_lshl_b32 s0, s37, 7
	v_writelane_b32 v254, s40, 13
	s_add_i32 s0, s0, s40
	v_writelane_b32 v254, s0, 14
	s_lshl_b32 s0, s14, 15
	v_writelane_b32 v254, s0, 15
	s_add_i32 s0, s0, 0x40000
	v_writelane_b32 v254, s0, 16
	v_writelane_b32 v254, s1, 17
	s_add_i32 s0, s1, 0x20000
	v_writelane_b32 v254, s0, 18
	s_lshl_b32 s0, s3, 7
	s_mul_i32 s2, s14, 0x5800
	v_writelane_b32 v254, s0, 19
	v_writelane_b32 v254, s2, 20
	s_add_i32 s0, s2, 0x2c000
	v_writelane_b32 v254, s0, 21
	s_add_i32 s0, 0, 0x22200
	v_writelane_b32 v254, s0, 22
	s_add_i32 s0, 0, 0x22204
	v_writelane_b32 v254, s0, 23
	v_writelane_b32 v254, s72, 24
	s_lshl_b64 s[56:57], s[4:5], 4
	s_lshl_b64 s[76:77], s[4:5], 3
	v_writelane_b32 v254, s73, 25
	v_writelane_b32 v254, s95, 26
	v_writelane_b32 v254, s58, 27
	v_writelane_b32 v254, s56, 28
	s_mov_b32 s1, 0xffff0000
	s_mov_b64 s[6:7], 0x80
	v_writelane_b32 v254, s57, 29
	s_mov_b32 s14, 0xbe11a98e
	s_mov_b64 s[62:63], s[76:77]
	v_writelane_b32 v254, s29, 30
	s_cmp_eq_u32 s86, 0
	s_cbranch_scc1 .LBB0_590
	s_branch .LBB0_87
